# first GEMM phase start-time stagger raised from 350 to 525 ticks per group step
# speedup vs baseline: 1.0118x; 1.0083x over previous
.LBB0_80:
	s_or_b64 exec, exec, s[28:29]
	s_bfe_u32 s6, s2, 0x20003
	s_cmp_lg_u32 s6, 0
	s_mov_b32 s39, 0
	s_waitcnt lgkmcnt(0)
	s_barrier
	s_cbranch_scc0 .LBB0_84
	s_memrealtime s[28:29]
	s_memrealtime s[16:17]
	s_mul_i32 s38, s6, 0x20d
	v_mov_b64_e32 v[0:1], s[38:39]
	s_waitcnt lgkmcnt(0)
	s_sub_u32 s6, s16, s28
	s_subb_u32 s7, s17, s29
	v_cmp_ge_u64_e32 vcc, s[6:7], v[0:1]
	s_cbranch_vccnz .LBB0_84
	v_mov_b64_e32 v[0:1], s[38:39]
